# PEER work split: gather waves 2 tokens, selecting waves 2 tokens per block (was 3 + 1)
# baseline (speedup 1.0000x reference)
.Lpeer_extra:
	s_setprio 0
	s_lshl_b32 s62, s49, 14
	s_sub_i32 s63, s52, s80
	s_lshl_b32 s63, s63, 4
	s_mov_b32 s61, 4
	s_mov_b32 s101, 15
	s_mov_b32 s100, 0
	s_mov_b64 s[34:35], 0
	v_add_u32_e32 v223, 4, v215
	s_branch .LBB0_732

.LBB0_728:
	s_add_i32 s52, s12, s80
	s_cmpk_lt_i32 s52, 0x300
	s_cselect_b64 s[10:11], -1, 0
	s_cmpk_gt_i32 s52, 0x2ff
	s_cselect_b64 s[26:27], -1, 0
	s_and_b64 s[28:29], s[6:7], s[10:11]
	s_lshl_b32 s53, s49, 14
	s_xor_b64 s[28:29], s[28:29], -1
	s_and_saveexec_b64 s[30:31], s[28:29]
	s_xor_b64 s[28:29], exec, s[30:31]
	s_cbranch_execz .LBB0_803
	s_and_saveexec_b64 s[30:31], s[8:9]
	s_cbranch_execz .LBB0_802
	s_and_b64 s[10:11], s[10:11], exec
	s_cselect_b32 s61, 4, 8
	s_cselect_b32 s101, 7, 15
	s_add_i32 s62, s53, 0
	s_lshl_b32 s63, s12, 4
	s_mov_b64 s[34:35], 0
	v_mov_b32_e32 v223, v215
	s_branch .LBB0_732
